# grid barrier: per-CU L1 invalidate issued right after the arrival (overlaps the wait / L2 writeback) instead of after the release
# speedup vs baseline: 1.0657x; 1.0109x over previous
.LBB0_53:
	s_or_b64 exec, exec, s[8:9]
	v_cvt_f32_u32_e32 v4, v2
	s_waitcnt vmcnt(0)
	v_readfirstlane_b32 s6, v3
	v_sub_u32_e32 v3, 0, v2
	v_rcp_iflag_f32_e32 v4, v4
	v_add_u32_e32 v5, s6, v1
	v_mul_f32_e32 v4, 0x4f7ffffe, v4
	v_cvt_u32_f32_e32 v4, v4
	v_mul_lo_u32 v1, v3, v4
	v_mul_hi_u32 v1, v4, v1
	v_add_u32_e32 v1, v4, v1
	v_mul_hi_u32 v1, v5, v1
	v_mul_lo_u32 v3, v1, v2
	v_sub_u32_e32 v3, v5, v3
	v_add_u32_e32 v4, 1, v1
	v_cmp_ge_u32_e32 vcc, v3, v2
	s_nop 1
	v_cndmask_b32_e32 v1, v1, v4, vcc
	v_sub_u32_e32 v4, v3, v2
	v_cndmask_b32_e32 v3, v3, v4, vcc
	v_add_u32_e32 v4, 1, v1
	v_cmp_ge_u32_e32 vcc, v3, v2
	v_add_u32_e32 v3, 1, v5
	s_nop 0
	v_cndmask_b32_e32 v1, v1, v4, vcc
	v_mul_lo_u32 v4, v2, v1
	v_add_u32_e32 v2, v4, v2
	v_cmp_ne_u32_e32 vcc, v3, v2
	s_and_saveexec_b64 s[6:7], vcc
	s_xor_b64 s[6:7], exec, s[6:7]
	s_cbranch_execz .LBB0_67
	s_waitcnt lgkmcnt(0)
	buffer_inv sc1
	v_mov_b32_e32 v0, 0x2000
	global_load_dword v0, v0, s[4:5] offset:1024 sc1
	s_add_u32 s12, s4, 0x2400
	s_addc_u32 s13, s5, 0
	s_waitcnt vmcnt(0)
	v_cmp_eq_u32_e32 vcc, v0, v1
	s_and_saveexec_b64 s[8:9], vcc
	s_cbranch_execz .LBB0_66
	s_add_u32 s10, s66, 0x1200
	s_addc_u32 s11, s67, 0
	s_mov_b32 s24, 1
	s_mov_b64 s[14:15], 0
	v_mov_b32_e32 v0, 0
	s_branch .LBB0_57

.LBB0_66:
	s_or_b64 exec, exec, s[8:9]
	s_waitcnt vmcnt(0)
	s_waitcnt vmcnt(0)
.LBB0_67:
	s_andn2_saveexec_b64 s[6:7], s[6:7]
	s_cbranch_execz .LBB0_87
	s_mov_b64 s[6:7], exec
	buffer_inv sc1
	buffer_wbl2 sc1
	s_waitcnt lgkmcnt(0)
	s_waitcnt vmcnt(0)
	v_mbcnt_lo_u32_b32 v1, s6, 0
	v_mbcnt_hi_u32_b32 v1, s7, v1
	v_cmp_eq_u32_e32 vcc, 0, v1
	s_and_saveexec_b64 s[8:9], vcc
	s_cbranch_execz .LBB0_70
	s_bcnt1_i32_b64 s6, s[6:7]
	v_mov_b32_e32 v2, 0x4000
	v_mov_b32_e32 v3, s6
	global_atomic_add v2, v2, v3, s[66:67] offset:1024 sc0

.LBB0_84:
	s_or_b64 exec, exec, s[6:7]
	s_mov_b64 s[6:7], exec
	v_mbcnt_lo_u32_b32 v0, s6, 0
	v_mbcnt_hi_u32_b32 v0, s7, v0
	v_cmp_eq_u32_e32 vcc, 0, v0
	s_waitcnt vmcnt(0)
	s_and_saveexec_b64 s[8:9], vcc
	s_cbranch_execz .LBB0_86
	s_bcnt1_i32_b64 s6, s[6:7]
	v_mov_b32_e32 v0, 0x2000
	v_mov_b32_e32 v1, s6
	global_atomic_add v0, v1, s[4:5] offset:1024

.LBB0_367:
	s_or_b64 exec, exec, s[8:9]
	v_cvt_f32_u32_e32 v4, v2
	s_waitcnt vmcnt(0)
	v_readfirstlane_b32 s6, v3
	v_sub_u32_e32 v3, 0, v2
	v_rcp_iflag_f32_e32 v4, v4
	v_add_u32_e32 v5, s6, v1
	v_mul_f32_e32 v4, 0x4f7ffffe, v4
	v_cvt_u32_f32_e32 v4, v4
	v_mul_lo_u32 v1, v3, v4
	v_mul_hi_u32 v1, v4, v1
	v_add_u32_e32 v1, v4, v1
	v_mul_hi_u32 v1, v5, v1
	v_mul_lo_u32 v3, v1, v2
	v_sub_u32_e32 v3, v5, v3
	v_add_u32_e32 v4, 1, v1
	v_cmp_ge_u32_e32 vcc, v3, v2
	s_nop 1
	v_cndmask_b32_e32 v1, v1, v4, vcc
	v_sub_u32_e32 v4, v3, v2
	v_cndmask_b32_e32 v3, v3, v4, vcc
	v_add_u32_e32 v4, 1, v1
	v_cmp_ge_u32_e32 vcc, v3, v2
	v_add_u32_e32 v3, 1, v5
	s_nop 0
	v_cndmask_b32_e32 v1, v1, v4, vcc
	v_mul_lo_u32 v4, v2, v1
	v_add_u32_e32 v2, v4, v2
	v_cmp_ne_u32_e32 vcc, v3, v2
	s_and_saveexec_b64 s[6:7], vcc
	s_xor_b64 s[6:7], exec, s[6:7]
	s_cbranch_execz .LBB0_381
	s_waitcnt lgkmcnt(0)
	buffer_inv sc1
	v_mov_b32_e32 v0, 0x2000
	global_load_dword v0, v0, s[4:5] offset:1024 sc1
	s_add_u32 s16, s4, 0x2400
	s_addc_u32 s17, s5, 0
	s_waitcnt vmcnt(0)
	v_cmp_eq_u32_e32 vcc, v0, v1
	s_and_saveexec_b64 s[8:9], vcc
	s_cbranch_execz .LBB0_380
	s_add_u32 s12, s66, 0x1200
	s_addc_u32 s13, s67, 0
	s_mov_b32 s28, 1
	s_mov_b64 s[18:19], 0
	v_mov_b32_e32 v0, 0
	s_branch .LBB0_371

.LBB0_573:
	s_or_b64 exec, exec, s[10:11]
	v_cvt_f32_u32_e32 v4, v2
	s_waitcnt vmcnt(0)
	v_readfirstlane_b32 s8, v3
	v_sub_u32_e32 v3, 0, v2
	v_rcp_iflag_f32_e32 v4, v4
	v_add_u32_e32 v5, s8, v1
	v_mul_f32_e32 v4, 0x4f7ffffe, v4
	v_cvt_u32_f32_e32 v4, v4
	v_mul_lo_u32 v1, v3, v4
	v_mul_hi_u32 v1, v4, v1
	v_add_u32_e32 v1, v4, v1
	v_mul_hi_u32 v1, v5, v1
	v_mul_lo_u32 v3, v1, v2
	v_sub_u32_e32 v3, v5, v3
	v_add_u32_e32 v4, 1, v1
	v_cmp_ge_u32_e32 vcc, v3, v2
	s_nop 1
	v_cndmask_b32_e32 v1, v1, v4, vcc
	v_sub_u32_e32 v4, v3, v2
	v_cndmask_b32_e32 v3, v3, v4, vcc
	v_add_u32_e32 v4, 1, v1
	v_cmp_ge_u32_e32 vcc, v3, v2
	v_add_u32_e32 v3, 1, v5
	s_nop 0
	v_cndmask_b32_e32 v1, v1, v4, vcc
	v_mul_lo_u32 v4, v2, v1
	v_add_u32_e32 v2, v4, v2
	v_cmp_ne_u32_e32 vcc, v3, v2
	s_and_saveexec_b64 s[8:9], vcc
	s_xor_b64 s[8:9], exec, s[8:9]
	s_cbranch_execz .LBB0_587
	s_waitcnt lgkmcnt(0)
	buffer_inv sc1
	v_mov_b32_e32 v0, 0x2000
	global_load_dword v0, v0, s[6:7] offset:1024 sc1
	s_add_u32 s16, s6, 0x2400
	s_addc_u32 s17, s7, 0
	s_waitcnt vmcnt(0)
	v_cmp_eq_u32_e32 vcc, v0, v1
	s_and_saveexec_b64 s[10:11], vcc
	s_cbranch_execz .LBB0_586
	s_add_u32 s12, s66, 0x1200
	s_addc_u32 s13, s67, 0
	s_mov_b32 s28, 1
	s_mov_b64 s[18:19], 0
	v_mov_b32_e32 v0, 0
	s_branch .LBB0_577

.LBB0_586:
	s_or_b64 exec, exec, s[10:11]
	s_waitcnt vmcnt(0)
	s_waitcnt vmcnt(0)
.LBB0_587:
	s_andn2_saveexec_b64 s[8:9], s[8:9]
	s_cbranch_execz .LBB0_607
	s_mov_b64 s[8:9], exec
	buffer_inv sc1
	buffer_wbl2 sc1
	s_waitcnt lgkmcnt(0)
	s_waitcnt vmcnt(0)
	v_mbcnt_lo_u32_b32 v1, s8, 0
	v_mbcnt_hi_u32_b32 v1, s9, v1
	v_cmp_eq_u32_e32 vcc, 0, v1
	s_and_saveexec_b64 s[10:11], vcc
	s_cbranch_execz .LBB0_590
	s_bcnt1_i32_b64 s8, s[8:9]
	v_mov_b32_e32 v2, 0x4000
	v_mov_b32_e32 v3, s8
	global_atomic_add v2, v2, v3, s[66:67] offset:1024 sc0

.LBB0_604:
	s_or_b64 exec, exec, s[8:9]
	s_mov_b64 s[8:9], exec
	v_mbcnt_lo_u32_b32 v0, s8, 0
	v_mbcnt_hi_u32_b32 v0, s9, v0
	v_cmp_eq_u32_e32 vcc, 0, v0
	s_waitcnt vmcnt(0)
	s_and_saveexec_b64 s[10:11], vcc
	s_cbranch_execz .LBB0_606
	s_bcnt1_i32_b64 s8, s[8:9]
	v_mov_b32_e32 v0, 0x2000
	v_mov_b32_e32 v1, s8
	global_atomic_add v0, v1, s[6:7] offset:1024

.LBB0_715:
	s_or_b64 exec, exec, s[12:13]
	v_cvt_f32_u32_e32 v4, v2
	s_waitcnt vmcnt(0)
	v_readfirstlane_b32 s10, v3
	v_sub_u32_e32 v3, 0, v2
	v_rcp_iflag_f32_e32 v4, v4
	v_add_u32_e32 v5, s10, v1
	v_mul_f32_e32 v4, 0x4f7ffffe, v4
	v_cvt_u32_f32_e32 v4, v4
	v_mul_lo_u32 v1, v3, v4
	v_mul_hi_u32 v1, v4, v1
	v_add_u32_e32 v1, v4, v1
	v_mul_hi_u32 v1, v5, v1
	v_mul_lo_u32 v3, v1, v2
	v_sub_u32_e32 v3, v5, v3
	v_add_u32_e32 v4, 1, v1
	v_cmp_ge_u32_e32 vcc, v3, v2
	s_nop 1
	v_cndmask_b32_e32 v1, v1, v4, vcc
	v_sub_u32_e32 v4, v3, v2
	v_cndmask_b32_e32 v3, v3, v4, vcc
	v_add_u32_e32 v4, 1, v1
	v_cmp_ge_u32_e32 vcc, v3, v2
	v_add_u32_e32 v3, 1, v5
	s_nop 0
	v_cndmask_b32_e32 v1, v1, v4, vcc
	v_mul_lo_u32 v4, v2, v1
	v_add_u32_e32 v2, v4, v2
	v_cmp_ne_u32_e32 vcc, v3, v2
	s_and_saveexec_b64 s[10:11], vcc
	s_xor_b64 s[10:11], exec, s[10:11]
	s_cbranch_execz .LBB0_729
	s_waitcnt lgkmcnt(0)
	buffer_inv sc1
	v_mov_b32_e32 v0, 0x2000
	global_load_dword v0, v0, s[6:7] offset:1024 sc1
	s_add_u32 s18, s6, 0x2400
	s_addc_u32 s19, s7, 0
	s_waitcnt vmcnt(0)
	v_cmp_eq_u32_e32 vcc, v0, v1
	s_and_saveexec_b64 s[12:13], vcc
	s_cbranch_execz .LBB0_728
	s_add_u32 s16, s66, 0x1200
	s_addc_u32 s17, s67, 0
	s_mov_b32 s30, 1
	s_mov_b64 s[20:21], 0
	v_mov_b32_e32 v0, 0
	s_branch .LBB0_719

.LBB0_728:
	s_or_b64 exec, exec, s[12:13]
	s_waitcnt vmcnt(0)
	s_waitcnt vmcnt(0)
.LBB0_729:
	s_andn2_saveexec_b64 s[10:11], s[10:11]
	s_cbranch_execz .LBB0_749
	s_mov_b64 s[10:11], exec
	buffer_inv sc1
	buffer_wbl2 sc1
	s_waitcnt lgkmcnt(0)
	s_waitcnt vmcnt(0)
	v_mbcnt_lo_u32_b32 v1, s10, 0
	v_mbcnt_hi_u32_b32 v1, s11, v1
	v_cmp_eq_u32_e32 vcc, 0, v1
	s_and_saveexec_b64 s[12:13], vcc
	s_cbranch_execz .LBB0_732
	s_bcnt1_i32_b64 s10, s[10:11]
	v_mov_b32_e32 v2, 0x4000
	v_mov_b32_e32 v3, s10
	global_atomic_add v2, v2, v3, s[66:67] offset:1024 sc0

.LBB0_746:
	s_or_b64 exec, exec, s[10:11]
	s_mov_b64 s[10:11], exec
	v_mbcnt_lo_u32_b32 v0, s10, 0
	v_mbcnt_hi_u32_b32 v0, s11, v0
	v_cmp_eq_u32_e32 vcc, 0, v0
	s_waitcnt vmcnt(0)
	s_and_saveexec_b64 s[12:13], vcc
	s_cbranch_execz .LBB0_748
	s_bcnt1_i32_b64 s10, s[10:11]
	v_mov_b32_e32 v0, 0x2000
	v_mov_b32_e32 v1, s10
	global_atomic_add v0, v1, s[6:7] offset:1024

.LBB0_972:
	s_or_b64 exec, exec, s[16:17]
	v_cvt_f32_u32_e32 v4, v2
	s_waitcnt vmcnt(0)
	v_readfirstlane_b32 s10, v3
	v_sub_u32_e32 v3, 0, v2
	v_rcp_iflag_f32_e32 v4, v4
	v_add_u32_e32 v5, s10, v1
	v_mul_f32_e32 v4, 0x4f7ffffe, v4
	v_cvt_u32_f32_e32 v4, v4
	v_mul_lo_u32 v1, v3, v4
	v_mul_hi_u32 v1, v4, v1
	v_add_u32_e32 v1, v4, v1
	v_mul_hi_u32 v1, v5, v1
	v_mul_lo_u32 v3, v1, v2
	v_sub_u32_e32 v3, v5, v3
	v_add_u32_e32 v4, 1, v1
	v_cmp_ge_u32_e32 vcc, v3, v2
	s_nop 1
	v_cndmask_b32_e32 v1, v1, v4, vcc
	v_sub_u32_e32 v4, v3, v2
	v_cndmask_b32_e32 v3, v3, v4, vcc
	v_add_u32_e32 v4, 1, v1
	v_cmp_ge_u32_e32 vcc, v3, v2
	v_add_u32_e32 v3, 1, v5
	s_nop 0
	v_cndmask_b32_e32 v1, v1, v4, vcc
	v_mul_lo_u32 v4, v2, v1
	v_add_u32_e32 v2, v4, v2
	v_cmp_ne_u32_e32 vcc, v3, v2
	s_and_saveexec_b64 s[10:11], vcc
	s_xor_b64 s[10:11], exec, s[10:11]
	s_cbranch_execz .LBB0_986
	s_waitcnt lgkmcnt(0)
	buffer_inv sc1
	v_mov_b32_e32 v0, 0x2000
	global_load_dword v0, v0, s[6:7] offset:1024 sc1
	s_add_u32 s20, s6, 0x2400
	s_addc_u32 s21, s7, 0
	s_waitcnt vmcnt(0)
	v_cmp_eq_u32_e32 vcc, v0, v1
	s_and_saveexec_b64 s[16:17], vcc
	s_cbranch_execz .LBB0_985
	s_add_u32 s18, s66, 0x1200
	s_addc_u32 s19, s67, 0
	s_mov_b32 s34, 1
	s_mov_b64 s[22:23], 0
	v_mov_b32_e32 v0, 0
	s_branch .LBB0_976

.LBB0_985:
	s_or_b64 exec, exec, s[16:17]
	s_waitcnt vmcnt(0)
	s_waitcnt vmcnt(0)
.LBB0_986:
	s_andn2_saveexec_b64 s[10:11], s[10:11]
	s_cbranch_execz .LBB0_1006
	s_mov_b64 s[10:11], exec
	buffer_inv sc1
	buffer_wbl2 sc1
	s_waitcnt lgkmcnt(0)
	s_waitcnt vmcnt(0)
	v_mbcnt_lo_u32_b32 v1, s10, 0
	v_mbcnt_hi_u32_b32 v1, s11, v1
	v_cmp_eq_u32_e32 vcc, 0, v1
	s_and_saveexec_b64 s[16:17], vcc
	s_cbranch_execz .LBB0_989
	s_bcnt1_i32_b64 s10, s[10:11]
	v_mov_b32_e32 v2, 0x4000
	v_mov_b32_e32 v3, s10
	global_atomic_add v2, v2, v3, s[66:67] offset:1024 sc0

.LBB0_1003:
	s_or_b64 exec, exec, s[10:11]
	s_mov_b64 s[10:11], exec
	v_mbcnt_lo_u32_b32 v0, s10, 0
	v_mbcnt_hi_u32_b32 v0, s11, v0
	v_cmp_eq_u32_e32 vcc, 0, v0
	s_waitcnt vmcnt(0)
	s_and_saveexec_b64 s[16:17], vcc
	s_cbranch_execz .LBB0_1005
	s_bcnt1_i32_b64 s10, s[10:11]
	v_mov_b32_e32 v0, 0x2000
	v_mov_b32_e32 v1, s10
	global_atomic_add v0, v1, s[6:7] offset:1024

.LBB0_1072:
	s_or_b64 exec, exec, s[16:17]
	v_cvt_f32_u32_e32 v4, v2
	s_waitcnt vmcnt(0)
	v_readfirstlane_b32 s12, v3
	v_sub_u32_e32 v3, 0, v2
	v_rcp_iflag_f32_e32 v4, v4
	v_add_u32_e32 v5, s12, v1
	v_mul_f32_e32 v4, 0x4f7ffffe, v4
	v_cvt_u32_f32_e32 v4, v4
	v_mul_lo_u32 v1, v3, v4
	v_mul_hi_u32 v1, v4, v1
	v_add_u32_e32 v1, v4, v1
	v_mul_hi_u32 v1, v5, v1
	v_mul_lo_u32 v3, v1, v2
	v_sub_u32_e32 v3, v5, v3
	v_add_u32_e32 v4, 1, v1
	v_cmp_ge_u32_e32 vcc, v3, v2
	s_nop 1
	v_cndmask_b32_e32 v1, v1, v4, vcc
	v_sub_u32_e32 v4, v3, v2
	v_cndmask_b32_e32 v3, v3, v4, vcc
	v_add_u32_e32 v4, 1, v1
	v_cmp_ge_u32_e32 vcc, v3, v2
	v_add_u32_e32 v3, 1, v5
	s_nop 0
	v_cndmask_b32_e32 v1, v1, v4, vcc
	v_mul_lo_u32 v4, v2, v1
	v_add_u32_e32 v2, v4, v2
	v_cmp_ne_u32_e32 vcc, v3, v2
	s_and_saveexec_b64 s[12:13], vcc
	s_xor_b64 s[12:13], exec, s[12:13]
	s_cbranch_execz .LBB0_1086
	s_waitcnt lgkmcnt(0)
	buffer_inv sc1
	v_mov_b32_e32 v0, 0x2000
	global_load_dword v0, v0, s[6:7] offset:1024 sc1
	s_add_u32 s20, s6, 0x2400
	s_addc_u32 s21, s7, 0
	s_waitcnt vmcnt(0)
	v_cmp_eq_u32_e32 vcc, v0, v1
	s_and_saveexec_b64 s[16:17], vcc
	s_cbranch_execz .LBB0_1085
	s_add_u32 s18, s66, 0x1200
	s_addc_u32 s19, s67, 0
	s_mov_b32 s34, 1
	s_mov_b64 s[22:23], 0
	v_mov_b32_e32 v0, 0
	s_branch .LBB0_1076

.LBB0_1086:
	s_andn2_saveexec_b64 s[12:13], s[12:13]
	s_cbranch_execz .LBB0_1106
	s_mov_b64 s[12:13], exec
	buffer_inv sc1
	buffer_wbl2 sc1
	s_waitcnt lgkmcnt(0)
	s_waitcnt vmcnt(0)
	v_mbcnt_lo_u32_b32 v1, s12, 0
	v_mbcnt_hi_u32_b32 v1, s13, v1
	v_cmp_eq_u32_e32 vcc, 0, v1
	s_and_saveexec_b64 s[16:17], vcc
	s_cbranch_execz .LBB0_1089
	s_bcnt1_i32_b64 s12, s[12:13]
	v_mov_b32_e32 v2, 0x4000
	v_mov_b32_e32 v3, s12
	global_atomic_add v2, v2, v3, s[66:67] offset:1024 sc0

.LBB0_1103:
	s_or_b64 exec, exec, s[12:13]
	s_mov_b64 s[12:13], exec
	v_mbcnt_lo_u32_b32 v0, s12, 0
	v_mbcnt_hi_u32_b32 v0, s13, v0
	v_cmp_eq_u32_e32 vcc, 0, v0
	s_waitcnt vmcnt(0)
	s_and_saveexec_b64 s[16:17], vcc
	s_cbranch_execz .LBB0_1105
	s_bcnt1_i32_b64 s12, s[12:13]
	v_mov_b32_e32 v0, 0x2000
	v_mov_b32_e32 v1, s12
	global_atomic_add v0, v1, s[6:7] offset:1024

.LBB0_1139:
	s_or_b64 exec, exec, s[16:17]
	v_cvt_f32_u32_e32 v4, v2
	s_waitcnt vmcnt(0)
	v_readfirstlane_b32 s14, v3
	v_sub_u32_e32 v3, 0, v2
	v_rcp_iflag_f32_e32 v4, v4
	v_add_u32_e32 v5, s14, v1
	v_mul_f32_e32 v4, 0x4f7ffffe, v4
	v_cvt_u32_f32_e32 v4, v4
	v_mul_lo_u32 v1, v3, v4
	v_mul_hi_u32 v1, v4, v1
	v_add_u32_e32 v1, v4, v1
	v_mul_hi_u32 v1, v5, v1
	v_mul_lo_u32 v3, v1, v2
	v_sub_u32_e32 v3, v5, v3
	v_add_u32_e32 v4, 1, v1
	v_cmp_ge_u32_e32 vcc, v3, v2
	s_nop 1
	v_cndmask_b32_e32 v1, v1, v4, vcc
	v_sub_u32_e32 v4, v3, v2
	v_cndmask_b32_e32 v3, v3, v4, vcc
	v_add_u32_e32 v4, 1, v1
	v_cmp_ge_u32_e32 vcc, v3, v2
	v_add_u32_e32 v3, 1, v5
	s_nop 0
	v_cndmask_b32_e32 v1, v1, v4, vcc
	v_mul_lo_u32 v4, v2, v1
	v_add_u32_e32 v2, v4, v2
	v_cmp_ne_u32_e32 vcc, v3, v2
	s_and_saveexec_b64 s[14:15], vcc
	s_xor_b64 s[14:15], exec, s[14:15]
	s_cbranch_execz .LBB0_1153
	s_waitcnt lgkmcnt(0)
	buffer_inv sc1
	v_mov_b32_e32 v0, 0x2000
	global_load_dword v0, v0, s[6:7] offset:1024 sc1
	s_add_u32 s20, s6, 0x2400
	s_addc_u32 s21, s7, 0
	s_waitcnt vmcnt(0)
	v_cmp_eq_u32_e32 vcc, v0, v1
	s_and_saveexec_b64 s[16:17], vcc
	s_cbranch_execz .LBB0_1152
	s_add_u32 s18, s66, 0x1200
	s_addc_u32 s19, s67, 0
	s_mov_b32 s34, 1
	s_mov_b64 s[22:23], 0
	v_mov_b32_e32 v0, 0
	s_branch .LBB0_1143

.LBB0_1153:
	s_andn2_saveexec_b64 s[14:15], s[14:15]
	s_cbranch_execz .LBB0_1173
	s_mov_b64 s[14:15], exec
	buffer_inv sc1
	buffer_wbl2 sc1
	s_waitcnt lgkmcnt(0)
	s_waitcnt vmcnt(0)
	v_mbcnt_lo_u32_b32 v1, s14, 0
	v_mbcnt_hi_u32_b32 v1, s15, v1
	v_cmp_eq_u32_e32 vcc, 0, v1
	s_and_saveexec_b64 s[16:17], vcc
	s_cbranch_execz .LBB0_1156
	s_bcnt1_i32_b64 s14, s[14:15]
	v_mov_b32_e32 v2, 0x4000
	v_mov_b32_e32 v3, s14
	global_atomic_add v2, v2, v3, s[66:67] offset:1024 sc0

.LBB0_1170:
	s_or_b64 exec, exec, s[14:15]
	s_mov_b64 s[14:15], exec
	v_mbcnt_lo_u32_b32 v0, s14, 0
	v_mbcnt_hi_u32_b32 v0, s15, v0
	v_cmp_eq_u32_e32 vcc, 0, v0
	s_waitcnt vmcnt(0)
	s_and_saveexec_b64 s[16:17], vcc
	s_cbranch_execz .LBB0_1172
	s_bcnt1_i32_b64 s14, s[14:15]
	v_mov_b32_e32 v0, 0x2000
	v_mov_b32_e32 v1, s14
	global_atomic_add v0, v1, s[6:7] offset:1024

.LBB0_1734:
	s_or_b64 exec, exec, s[18:19]
	v_cvt_f32_u32_e32 v4, v2
	s_waitcnt vmcnt(0)
	v_readfirstlane_b32 s16, v3
	v_sub_u32_e32 v3, 0, v2
	v_rcp_iflag_f32_e32 v4, v4
	v_add_u32_e32 v5, s16, v1
	v_mul_f32_e32 v4, 0x4f7ffffe, v4
	v_cvt_u32_f32_e32 v4, v4
	v_mul_lo_u32 v1, v3, v4
	v_mul_hi_u32 v1, v4, v1
	v_add_u32_e32 v1, v4, v1
	v_mul_hi_u32 v1, v5, v1
	v_mul_lo_u32 v3, v1, v2
	v_sub_u32_e32 v3, v5, v3
	v_add_u32_e32 v4, 1, v1
	v_cmp_ge_u32_e32 vcc, v3, v2
	s_nop 1
	v_cndmask_b32_e32 v1, v1, v4, vcc
	v_sub_u32_e32 v4, v3, v2
	v_cndmask_b32_e32 v3, v3, v4, vcc
	v_add_u32_e32 v4, 1, v1
	v_cmp_ge_u32_e32 vcc, v3, v2
	v_add_u32_e32 v3, 1, v5
	s_nop 0
	v_cndmask_b32_e32 v1, v1, v4, vcc
	v_mul_lo_u32 v4, v2, v1
	v_add_u32_e32 v2, v4, v2
	v_cmp_ne_u32_e32 vcc, v3, v2
	s_and_saveexec_b64 s[16:17], vcc
	s_xor_b64 s[16:17], exec, s[16:17]
	s_cbranch_execz .LBB0_1748
	s_waitcnt lgkmcnt(0)
	buffer_inv sc1
	v_mov_b32_e32 v0, 0x2000
	global_load_dword v0, v0, s[14:15] offset:1024 sc1
	s_add_u32 s22, s14, 0x2400
	s_addc_u32 s23, s15, 0
	s_waitcnt vmcnt(0)
	v_cmp_eq_u32_e32 vcc, v0, v1
	s_and_saveexec_b64 s[18:19], vcc
	s_cbranch_execz .LBB0_1747
	s_add_u32 s20, s66, 0x1200
	s_addc_u32 s21, s67, 0
	s_mov_b32 s36, 1
	s_mov_b64 s[24:25], 0
	v_mov_b32_e32 v0, 0
	s_branch .LBB0_1738

.LBB0_1747:
	s_or_b64 exec, exec, s[18:19]
	s_waitcnt vmcnt(0)
	s_waitcnt vmcnt(0)
.LBB0_1748:
	s_andn2_saveexec_b64 s[16:17], s[16:17]
	s_cbranch_execz .LBB0_1768
	s_mov_b64 s[16:17], exec
	buffer_inv sc1
	buffer_wbl2 sc1
	s_waitcnt lgkmcnt(0)
	s_waitcnt vmcnt(0)
	v_mbcnt_lo_u32_b32 v1, s16, 0
	v_mbcnt_hi_u32_b32 v1, s17, v1
	v_cmp_eq_u32_e32 vcc, 0, v1
	s_and_saveexec_b64 s[18:19], vcc
	s_cbranch_execz .LBB0_1751
	s_bcnt1_i32_b64 s16, s[16:17]
	v_mov_b32_e32 v2, 0x4000
	v_mov_b32_e32 v3, s16
	global_atomic_add v2, v2, v3, s[66:67] offset:1024 sc0

.LBB0_1765:
	s_or_b64 exec, exec, s[16:17]
	s_mov_b64 s[16:17], exec
	v_mbcnt_lo_u32_b32 v0, s16, 0
	v_mbcnt_hi_u32_b32 v0, s17, v0
	v_cmp_eq_u32_e32 vcc, 0, v0
	s_waitcnt vmcnt(0)
	s_and_saveexec_b64 s[18:19], vcc
	s_cbranch_execz .LBB0_1767
	s_bcnt1_i32_b64 s16, s[16:17]
	v_mov_b32_e32 v0, 0x2000
	v_mov_b32_e32 v1, s16
	global_atomic_add v0, v1, s[14:15] offset:1024

.LBB0_2325:
	s_or_b64 exec, exec, s[16:17]
	v_cvt_f32_u32_e32 v4, v2
	s_waitcnt vmcnt(0)
	v_readfirstlane_b32 s14, v3
	v_sub_u32_e32 v3, 0, v2
	v_rcp_iflag_f32_e32 v4, v4
	v_add_u32_e32 v5, s14, v1
	v_mul_f32_e32 v4, 0x4f7ffffe, v4
	v_cvt_u32_f32_e32 v4, v4
	v_mul_lo_u32 v1, v3, v4
	v_mul_hi_u32 v1, v4, v1
	v_add_u32_e32 v1, v4, v1
	v_mul_hi_u32 v1, v5, v1
	v_mul_lo_u32 v3, v1, v2
	v_sub_u32_e32 v3, v5, v3
	v_add_u32_e32 v4, 1, v1
	v_cmp_ge_u32_e32 vcc, v3, v2
	s_nop 1
	v_cndmask_b32_e32 v1, v1, v4, vcc
	v_sub_u32_e32 v4, v3, v2
	v_cndmask_b32_e32 v3, v3, v4, vcc
	v_add_u32_e32 v4, 1, v1
	v_cmp_ge_u32_e32 vcc, v3, v2
	v_add_u32_e32 v3, 1, v5
	s_nop 0
	v_cndmask_b32_e32 v1, v1, v4, vcc
	v_mul_lo_u32 v4, v2, v1
	v_add_u32_e32 v2, v4, v2
	v_cmp_ne_u32_e32 vcc, v3, v2
	s_and_saveexec_b64 s[14:15], vcc
	s_xor_b64 s[14:15], exec, s[14:15]
	s_cbranch_execz .LBB0_2339
	s_waitcnt lgkmcnt(0)
	buffer_inv sc1
	v_mov_b32_e32 v0, 0x2000
	global_load_dword v0, v0, s[8:9] offset:1024 sc1
	s_add_u32 s20, s8, 0x2400
	s_addc_u32 s21, s9, 0
	s_waitcnt vmcnt(0)
	v_cmp_eq_u32_e32 vcc, v0, v1
	s_and_saveexec_b64 s[16:17], vcc
	s_cbranch_execz .LBB0_2338
	s_add_u32 s18, s66, 0x1200
	s_addc_u32 s19, s67, 0
	s_mov_b32 s34, 1
	s_mov_b64 s[22:23], 0
	v_mov_b32_e32 v0, 0
	s_branch .LBB0_2329

.LBB0_2356:
	s_or_b64 exec, exec, s[14:15]
	s_mov_b64 s[14:15], exec
	v_mbcnt_lo_u32_b32 v0, s14, 0
	v_mbcnt_hi_u32_b32 v0, s15, v0
	v_cmp_eq_u32_e32 vcc, 0, v0
	s_waitcnt vmcnt(0)
	s_and_saveexec_b64 s[16:17], vcc
	s_cbranch_execz .LBB0_2358
	s_bcnt1_i32_b64 s14, s[14:15]
	v_mov_b32_e32 v0, 0x2000
	v_mov_b32_e32 v1, s14
	global_atomic_add v0, v1, s[8:9] offset:1024

.LBB0_2682:
	s_or_b64 exec, exec, s[14:15]
	v_cvt_f32_u32_e32 v4, v2
	s_waitcnt vmcnt(0)
	v_readfirstlane_b32 s10, v3
	v_sub_u32_e32 v3, 0, v2
	v_rcp_iflag_f32_e32 v4, v4
	v_add_u32_e32 v5, s10, v1
	v_mul_f32_e32 v4, 0x4f7ffffe, v4
	v_cvt_u32_f32_e32 v4, v4
	v_mul_lo_u32 v1, v3, v4
	v_mul_hi_u32 v1, v4, v1
	v_add_u32_e32 v1, v4, v1
	v_mul_hi_u32 v1, v5, v1
	v_mul_lo_u32 v3, v1, v2
	v_sub_u32_e32 v3, v5, v3
	v_add_u32_e32 v4, 1, v1
	v_cmp_ge_u32_e32 vcc, v3, v2
	s_nop 1
	v_cndmask_b32_e32 v1, v1, v4, vcc
	v_sub_u32_e32 v4, v3, v2
	v_cndmask_b32_e32 v3, v3, v4, vcc
	v_add_u32_e32 v4, 1, v1
	v_cmp_ge_u32_e32 vcc, v3, v2
	v_add_u32_e32 v3, 1, v5
	s_nop 0
	v_cndmask_b32_e32 v1, v1, v4, vcc
	v_mul_lo_u32 v4, v2, v1
	v_add_u32_e32 v2, v4, v2
	v_cmp_ne_u32_e32 vcc, v3, v2
	s_and_saveexec_b64 s[10:11], vcc
	s_xor_b64 s[10:11], exec, s[10:11]
	s_cbranch_execz .LBB0_2696
	s_waitcnt lgkmcnt(0)
	buffer_inv sc1
	v_mov_b32_e32 v0, 0x2000
	global_load_dword v0, v0, s[8:9] offset:1024 sc1
	s_add_u32 s18, s8, 0x2400
	s_addc_u32 s19, s9, 0
	s_waitcnt vmcnt(0)
	v_cmp_eq_u32_e32 vcc, v0, v1
	s_and_saveexec_b64 s[14:15], vcc
	s_cbranch_execz .LBB0_2695
	s_add_u32 s16, s66, 0x1200
	s_addc_u32 s17, s67, 0
	s_mov_b32 s30, 1
	s_mov_b64 s[20:21], 0
	v_mov_b32_e32 v0, 0
	s_branch .LBB0_2686

.LBB0_2695:
	s_or_b64 exec, exec, s[14:15]
	s_waitcnt vmcnt(0)
	s_waitcnt vmcnt(0)
.LBB0_2696:
	s_andn2_saveexec_b64 s[10:11], s[10:11]
	s_cbranch_execz .LBB0_2716
	s_mov_b64 s[10:11], exec
	buffer_inv sc1
	buffer_wbl2 sc1
	s_waitcnt lgkmcnt(0)
	s_waitcnt vmcnt(0)
	v_mbcnt_lo_u32_b32 v1, s10, 0
	v_mbcnt_hi_u32_b32 v1, s11, v1
	v_cmp_eq_u32_e32 vcc, 0, v1
	s_and_saveexec_b64 s[14:15], vcc
	s_cbranch_execz .LBB0_2699
	s_bcnt1_i32_b64 s10, s[10:11]
	v_mov_b32_e32 v2, 0x4000
	v_mov_b32_e32 v3, s10
	global_atomic_add v2, v2, v3, s[66:67] offset:1024 sc0

.LBB0_2713:
	s_or_b64 exec, exec, s[10:11]
	s_mov_b64 s[10:11], exec
	v_mbcnt_lo_u32_b32 v0, s10, 0
	v_mbcnt_hi_u32_b32 v0, s11, v0
	v_cmp_eq_u32_e32 vcc, 0, v0
	s_waitcnt vmcnt(0)
	s_and_saveexec_b64 s[14:15], vcc
	s_cbranch_execz .LBB0_2715
	s_bcnt1_i32_b64 s10, s[10:11]
	v_mov_b32_e32 v0, 0x2000
	v_mov_b32_e32 v1, s10
	global_atomic_add v0, v1, s[8:9] offset:1024

.LBB0_2749:
	s_or_b64 exec, exec, s[12:13]
	v_cvt_f32_u32_e32 v4, v2
	s_waitcnt vmcnt(0)
	v_readfirstlane_b32 s10, v3
	v_sub_u32_e32 v3, 0, v2
	v_rcp_iflag_f32_e32 v4, v4
	v_add_u32_e32 v5, s10, v1
	v_mul_f32_e32 v4, 0x4f7ffffe, v4
	v_cvt_u32_f32_e32 v4, v4
	v_mul_lo_u32 v1, v3, v4
	v_mul_hi_u32 v1, v4, v1
	v_add_u32_e32 v1, v4, v1
	v_mul_hi_u32 v1, v5, v1
	v_mul_lo_u32 v3, v1, v2
	v_sub_u32_e32 v3, v5, v3
	v_add_u32_e32 v4, 1, v1
	v_cmp_ge_u32_e32 vcc, v3, v2
	s_nop 1
	v_cndmask_b32_e32 v1, v1, v4, vcc
	v_sub_u32_e32 v4, v3, v2
	v_cndmask_b32_e32 v3, v3, v4, vcc
	v_add_u32_e32 v4, 1, v1
	v_cmp_ge_u32_e32 vcc, v3, v2
	v_add_u32_e32 v3, 1, v5
	s_nop 0
	v_cndmask_b32_e32 v1, v1, v4, vcc
	v_mul_lo_u32 v4, v2, v1
	v_add_u32_e32 v2, v4, v2
	v_cmp_ne_u32_e32 vcc, v3, v2
	s_and_saveexec_b64 s[10:11], vcc
	s_xor_b64 s[10:11], exec, s[10:11]
	s_cbranch_execz .LBB0_2763
	s_waitcnt lgkmcnt(0)
	buffer_inv sc1
	v_mov_b32_e32 v0, 0x2000
	global_load_dword v0, v0, s[8:9] offset:1024 sc1
	s_add_u32 s16, s8, 0x2400
	s_addc_u32 s17, s9, 0
	s_waitcnt vmcnt(0)
	v_cmp_eq_u32_e32 vcc, v0, v1
	s_and_saveexec_b64 s[12:13], vcc
	s_cbranch_execz .LBB0_2762
	s_add_u32 s14, s66, 0x1200
	s_addc_u32 s15, s67, 0
	s_mov_b32 s28, 1
	s_mov_b64 s[18:19], 0
	v_mov_b32_e32 v0, 0
	s_branch .LBB0_2753

.LBB0_2780:
	s_or_b64 exec, exec, s[10:11]
	s_mov_b64 s[10:11], exec
	v_mbcnt_lo_u32_b32 v0, s10, 0
	v_mbcnt_hi_u32_b32 v0, s11, v0
	v_cmp_eq_u32_e32 vcc, 0, v0
	s_waitcnt vmcnt(0)
	s_and_saveexec_b64 s[12:13], vcc
	s_cbranch_execz .LBB0_2782
	s_bcnt1_i32_b64 s10, s[10:11]
	v_mov_b32_e32 v0, 0x2000
	v_mov_b32_e32 v1, s10
	global_atomic_add v0, v1, s[8:9] offset:1024

.LBB0_3344:
	s_or_b64 exec, exec, s[10:11]
	v_cvt_f32_u32_e32 v4, v2
	s_waitcnt vmcnt(0)
	v_readfirstlane_b32 s8, v3
	v_sub_u32_e32 v3, 0, v2
	v_rcp_iflag_f32_e32 v4, v4
	v_add_u32_e32 v5, s8, v1
	v_mul_f32_e32 v4, 0x4f7ffffe, v4
	v_cvt_u32_f32_e32 v4, v4
	v_mul_lo_u32 v1, v3, v4
	v_mul_hi_u32 v1, v4, v1
	v_add_u32_e32 v1, v4, v1
	v_mul_hi_u32 v1, v5, v1
	v_mul_lo_u32 v3, v1, v2
	v_sub_u32_e32 v3, v5, v3
	v_add_u32_e32 v4, 1, v1
	v_cmp_ge_u32_e32 vcc, v3, v2
	s_nop 1
	v_cndmask_b32_e32 v1, v1, v4, vcc
	v_sub_u32_e32 v4, v3, v2
	v_cndmask_b32_e32 v3, v3, v4, vcc
	v_add_u32_e32 v4, 1, v1
	v_cmp_ge_u32_e32 vcc, v3, v2
	v_add_u32_e32 v3, 1, v5
	s_nop 0
	v_cndmask_b32_e32 v1, v1, v4, vcc
	v_mul_lo_u32 v4, v2, v1
	v_add_u32_e32 v2, v4, v2
	v_cmp_ne_u32_e32 vcc, v3, v2
	s_and_saveexec_b64 s[8:9], vcc
	s_xor_b64 s[8:9], exec, s[8:9]
	s_cbranch_execz .LBB0_3358
	s_waitcnt lgkmcnt(0)
	buffer_inv sc1
	v_mov_b32_e32 v0, 0x2000
	global_load_dword v0, v0, s[6:7] offset:1024 sc1
	s_add_u32 s14, s6, 0x2400
	s_addc_u32 s15, s7, 0
	s_waitcnt vmcnt(0)
	v_cmp_eq_u32_e32 vcc, v0, v1
	s_and_saveexec_b64 s[10:11], vcc
	s_cbranch_execz .LBB0_3357
	s_add_u32 s12, s66, 0x1200
	s_addc_u32 s13, s67, 0
	s_mov_b32 s26, 1
	s_mov_b64 s[16:17], 0
	v_mov_b32_e32 v0, 0
	s_branch .LBB0_3348

.LBB0_3442:
	s_or_b64 exec, exec, s[6:7]
	v_cvt_f32_u32_e32 v4, v2
	s_waitcnt vmcnt(0)
	v_readfirstlane_b32 s4, v3
	v_sub_u32_e32 v3, 0, v2
	v_rcp_iflag_f32_e32 v4, v4
	v_add_u32_e32 v5, s4, v1
	v_mul_f32_e32 v4, 0x4f7ffffe, v4
	v_cvt_u32_f32_e32 v4, v4
	v_mul_lo_u32 v1, v3, v4
	v_mul_hi_u32 v1, v4, v1
	v_add_u32_e32 v1, v4, v1
	v_mul_hi_u32 v1, v5, v1
	v_mul_lo_u32 v3, v1, v2
	v_sub_u32_e32 v3, v5, v3
	v_add_u32_e32 v4, 1, v1
	v_cmp_ge_u32_e32 vcc, v3, v2
	s_nop 1
	v_cndmask_b32_e32 v1, v1, v4, vcc
	v_sub_u32_e32 v4, v3, v2
	v_cndmask_b32_e32 v3, v3, v4, vcc
	v_add_u32_e32 v4, 1, v1
	v_cmp_ge_u32_e32 vcc, v3, v2
	v_add_u32_e32 v3, 1, v5
	s_nop 0
	v_cndmask_b32_e32 v1, v1, v4, vcc
	v_mul_lo_u32 v4, v2, v1
	v_add_u32_e32 v2, v4, v2
	v_cmp_ne_u32_e32 vcc, v3, v2
	s_and_saveexec_b64 s[4:5], vcc
	s_xor_b64 s[4:5], exec, s[4:5]
	s_cbranch_execz .LBB0_3456
	s_waitcnt lgkmcnt(0)
	buffer_inv sc1
	v_mov_b32_e32 v0, 0x2000
	global_load_dword v0, v0, s[2:3] offset:1024 sc1
	s_add_u32 s10, s2, 0x2400
	s_addc_u32 s11, s3, 0
	s_waitcnt vmcnt(0)
	v_cmp_eq_u32_e32 vcc, v0, v1
	s_and_saveexec_b64 s[6:7], vcc
	s_cbranch_execz .LBB0_3455
	s_add_u32 s8, s66, 0x1200
	s_addc_u32 s9, s67, 0
	s_mov_b32 s22, 1
	s_mov_b64 s[12:13], 0
	v_mov_b32_e32 v0, 0
	s_branch .LBB0_3446

.LBB0_3455:
	s_or_b64 exec, exec, s[6:7]
	s_waitcnt vmcnt(0)
	s_waitcnt vmcnt(0)
.LBB0_3456:
	s_andn2_saveexec_b64 s[4:5], s[4:5]
	s_cbranch_execz .LBB0_3476
	s_mov_b64 s[4:5], exec
	buffer_inv sc1
	buffer_wbl2 sc1
	s_waitcnt lgkmcnt(0)
	s_waitcnt vmcnt(0)
	v_mbcnt_lo_u32_b32 v1, s4, 0
	v_mbcnt_hi_u32_b32 v1, s5, v1
	v_cmp_eq_u32_e32 vcc, 0, v1
	s_and_saveexec_b64 s[6:7], vcc
	s_cbranch_execz .LBB0_3459
	s_bcnt1_i32_b64 s4, s[4:5]
	v_mov_b32_e32 v2, 0x4000
	v_mov_b32_e32 v3, s4
	global_atomic_add v2, v2, v3, s[66:67] offset:1024 sc0

.LBB0_3473:
	s_or_b64 exec, exec, s[4:5]
	s_mov_b64 s[4:5], exec
	v_mbcnt_lo_u32_b32 v0, s4, 0
	v_mbcnt_hi_u32_b32 v0, s5, v0
	v_cmp_eq_u32_e32 vcc, 0, v0
	s_waitcnt vmcnt(0)
	s_and_saveexec_b64 s[6:7], vcc
	s_cbranch_execz .LBB0_3475
	s_bcnt1_i32_b64 s4, s[4:5]
	v_mov_b32_e32 v0, 0x2000
	v_mov_b32_e32 v1, s4
	global_atomic_add v0, v1, s[2:3] offset:1024
